# same scalar-base LDS-DMA addressing in the in-proj, out-proj and FFN-down GEMM K-loops
# speedup vs baseline: 1.1515x; 1.0055x over previous
.LBB0_150:
	ds_read_b128 v[130:133], v220
	ds_read_b128 v[134:137], v220 offset:1024
	ds_read_b128 v[138:141], v220 offset:2048
	ds_read_b128 v[142:145], v220 offset:3072
	ds_read_b128 v[164:167], v221
	ds_read_b128 v[168:171], v221 offset:1024
	ds_read_b128 v[172:175], v221 offset:2048
	ds_read_b128 v[176:179], v221 offset:3072
	s_add_u32 s28, s6, 0xfff80080
	s_addc_u32 s29, s7, -1
	s_cmp_eq_u32 s35, 28
	s_cselect_b32 s31, s1, s29
	s_cselect_b32 s30, s5, s28
	s_cselect_b32 s29, s21, s34
	s_cselect_b32 s28, s23, s33
	s_add_i32 m0, s40, 0xc000
	ds_read_b128 v[180:183], v222
	ds_read_b128 v[184:187], v222 offset:1024
	ds_read_b128 v[188:191], v222 offset:2048
	ds_read_b128 v[192:195], v222 offset:3072
	ds_read_b128 v[196:199], v222 offset:4096
	ds_read_b128 v[200:203], v222 offset:5120
	ds_read_b128 v[204:207], v222 offset:6144
	ds_read_b128 v[208:211], v222 offset:7168
	global_load_lds_dwordx4 v156, s[6:7]
	s_add_i32 m0, s40, 0xe000
	s_nop 0
	global_load_lds_dwordx4 v158, s[6:7]
	s_waitcnt vmcnt(8)
	s_waitcnt lgkmcnt(0)
	s_barrier
	s_setprio 1
	s_waitcnt lgkmcnt(0)
	v_mfma_f32_16x16x32_bf16 v[126:129], v[130:133], v[180:183], v[126:129]
	v_mfma_f32_16x16x32_bf16 v[122:125], v[138:141], v[180:183], v[122:125]
	v_mfma_f32_16x16x32_bf16 v[110:113], v[130:133], v[188:191], v[110:113]
	v_mfma_f32_16x16x32_bf16 v[106:109], v[138:141], v[188:191], v[106:109]
	v_mfma_f32_16x16x32_bf16 v[94:97], v[130:133], v[196:199], v[94:97]
	v_mfma_f32_16x16x32_bf16 v[90:93], v[138:141], v[196:199], v[90:93]
	v_mfma_f32_16x16x32_bf16 v[78:81], v[130:133], v[204:207], v[78:81]
	v_mfma_f32_16x16x32_bf16 v[74:77], v[138:141], v[204:207], v[74:77]
	v_mfma_f32_16x16x32_bf16 v[126:129], v[134:137], v[184:187], v[126:129]
	v_mfma_f32_16x16x32_bf16 v[122:125], v[142:145], v[184:187], v[122:125]
	v_mfma_f32_16x16x32_bf16 v[110:113], v[134:137], v[192:195], v[110:113]
	v_mfma_f32_16x16x32_bf16 v[106:109], v[142:145], v[192:195], v[106:109]
	v_mfma_f32_16x16x32_bf16 v[94:97], v[134:137], v[200:203], v[94:97]
	v_mfma_f32_16x16x32_bf16 v[90:93], v[142:145], v[200:203], v[90:93]
	v_mfma_f32_16x16x32_bf16 v[78:81], v[134:137], v[208:211], v[78:81]
	v_mfma_f32_16x16x32_bf16 v[74:77], v[142:145], v[208:211], v[74:77]
	s_setprio 0
	s_setprio 1
	v_mfma_f32_16x16x32_bf16 v[118:121], v[164:167], v[180:183], v[118:121]
	v_mfma_f32_16x16x32_bf16 v[114:117], v[172:175], v[180:183], v[114:117]
	v_mfma_f32_16x16x32_bf16 v[102:105], v[164:167], v[188:191], v[102:105]
	v_mfma_f32_16x16x32_bf16 v[98:101], v[172:175], v[188:191], v[98:101]
	v_mfma_f32_16x16x32_bf16 v[86:89], v[164:167], v[196:199], v[86:89]
	v_mfma_f32_16x16x32_bf16 v[82:85], v[172:175], v[196:199], v[82:85]
	v_mfma_f32_16x16x32_bf16 v[70:73], v[164:167], v[204:207], v[70:73]
	v_mfma_f32_16x16x32_bf16 v[66:69], v[172:175], v[204:207], v[66:69]
	v_mfma_f32_16x16x32_bf16 v[118:121], v[168:171], v[184:187], v[118:121]
	v_mfma_f32_16x16x32_bf16 v[114:117], v[176:179], v[184:187], v[114:117]
	v_mfma_f32_16x16x32_bf16 v[102:105], v[168:171], v[192:195], v[102:105]
	v_mfma_f32_16x16x32_bf16 v[98:101], v[176:179], v[192:195], v[98:101]
	v_mfma_f32_16x16x32_bf16 v[86:89], v[168:171], v[200:203], v[86:89]
	v_mfma_f32_16x16x32_bf16 v[82:85], v[176:179], v[200:203], v[82:85]
	v_mfma_f32_16x16x32_bf16 v[70:73], v[168:171], v[208:211], v[70:73]
	v_mfma_f32_16x16x32_bf16 v[66:69], v[176:179], v[208:211], v[66:69]
	s_setprio 0
	s_barrier
	s_add_i32 s68, s94, s39
	s_mov_b32 m0, s68
	ds_read_b128 v[180:183], v222 offset:16384
	ds_read_b128 v[184:187], v222 offset:17408
	ds_read_b128 v[188:191], v222 offset:18432
	ds_read_b128 v[192:195], v222 offset:19456
	ds_read_b128 v[196:199], v222 offset:20480
	ds_read_b128 v[200:203], v222 offset:21504
	ds_read_b128 v[204:207], v222 offset:22528
	ds_read_b128 v[208:211], v222 offset:23552
	global_load_lds_dwordx4 v148, s[28:29]
	s_add_i32 m0, s68, 0x2000
	s_add_u32 s68, s28, 0x80000
	s_addc_u32 s69, s29, 0
	s_add_i32 s70, s96, s39
	global_load_lds_dwordx4 v152, s[28:29]
	s_mov_b32 m0, s70
	s_nop 0
	global_load_lds_dwordx4 v148, s[68:69]
	s_add_i32 m0, s70, 0x2000
	s_nop 0
	global_load_lds_dwordx4 v152, s[68:69]
	s_mov_b32 m0, s40
	s_nop 0
	global_load_lds_dwordx4 v146, s[30:31]
	s_mov_b32 m0, s41
	s_nop 0
	global_load_lds_dwordx4 v150, s[30:31]
	s_waitcnt vmcnt(8)
	s_waitcnt lgkmcnt(0)
	s_barrier
	s_setprio 1
	s_waitcnt lgkmcnt(0)
	v_mfma_f32_16x16x32_bf16 v[62:65], v[130:133], v[180:183], v[62:65]
	v_mfma_f32_16x16x32_bf16 v[58:61], v[138:141], v[180:183], v[58:61]
	v_mfma_f32_16x16x32_bf16 v[46:49], v[130:133], v[188:191], v[46:49]
	v_mfma_f32_16x16x32_bf16 v[42:45], v[138:141], v[188:191], v[42:45]
	v_mfma_f32_16x16x32_bf16 v[30:33], v[130:133], v[196:199], v[30:33]
	v_mfma_f32_16x16x32_bf16 v[26:29], v[138:141], v[196:199], v[26:29]
	v_mfma_f32_16x16x32_bf16 v[14:17], v[130:133], v[204:207], v[14:17]
	v_mfma_f32_16x16x32_bf16 v[10:13], v[138:141], v[204:207], v[10:13]
	v_mfma_f32_16x16x32_bf16 v[62:65], v[134:137], v[184:187], v[62:65]
	v_mfma_f32_16x16x32_bf16 v[58:61], v[142:145], v[184:187], v[58:61]
	v_mfma_f32_16x16x32_bf16 v[46:49], v[134:137], v[192:195], v[46:49]
	v_mfma_f32_16x16x32_bf16 v[42:45], v[142:145], v[192:195], v[42:45]
	v_mfma_f32_16x16x32_bf16 v[30:33], v[134:137], v[200:203], v[30:33]
	v_mfma_f32_16x16x32_bf16 v[26:29], v[142:145], v[200:203], v[26:29]
	v_mfma_f32_16x16x32_bf16 v[14:17], v[134:137], v[208:211], v[14:17]
	v_mfma_f32_16x16x32_bf16 v[10:13], v[142:145], v[208:211], v[10:13]
	s_setprio 0
	s_setprio 1
	v_mfma_f32_16x16x32_bf16 v[54:57], v[164:167], v[180:183], v[54:57]
	v_mfma_f32_16x16x32_bf16 v[50:53], v[172:175], v[180:183], v[50:53]
	v_mfma_f32_16x16x32_bf16 v[38:41], v[164:167], v[188:191], v[38:41]
	v_mfma_f32_16x16x32_bf16 v[34:37], v[172:175], v[188:191], v[34:37]
	v_mfma_f32_16x16x32_bf16 v[22:25], v[164:167], v[196:199], v[22:25]
	v_mfma_f32_16x16x32_bf16 v[18:21], v[172:175], v[196:199], v[18:21]
	v_mfma_f32_16x16x32_bf16 v[6:9], v[164:167], v[204:207], v[6:9]
	v_mfma_f32_16x16x32_bf16 v[2:5], v[172:175], v[204:207], v[2:5]
	v_mfma_f32_16x16x32_bf16 v[54:57], v[168:171], v[184:187], v[54:57]
	v_mfma_f32_16x16x32_bf16 v[50:53], v[176:179], v[184:187], v[50:53]
	v_mfma_f32_16x16x32_bf16 v[38:41], v[168:171], v[192:195], v[38:41]
	v_mfma_f32_16x16x32_bf16 v[34:37], v[176:179], v[192:195], v[34:37]
	v_mfma_f32_16x16x32_bf16 v[22:25], v[168:171], v[200:203], v[22:25]
	v_mfma_f32_16x16x32_bf16 v[18:21], v[176:179], v[200:203], v[18:21]
	v_mfma_f32_16x16x32_bf16 v[6:9], v[168:171], v[208:211], v[6:9]
	v_mfma_f32_16x16x32_bf16 v[2:5], v[176:179], v[208:211], v[2:5]
	s_setprio 0
	s_barrier
	s_add_i32 s68, 0, 0x18000
	s_add_i32 s69, 0, 0x1c000
	v_add_u32_e32 v142, s68, v218
	v_add_u32_e32 v154, s69, v218
	ds_read_b128 v[130:133], v142
	ds_read_b128 v[134:137], v142 offset:1024
	ds_read_b128 v[138:141], v142 offset:2048
	ds_read_b128 v[142:145], v142 offset:3072
	ds_read_b128 v[164:167], v154
	ds_read_b128 v[168:171], v154 offset:1024
	ds_read_b128 v[172:175], v154 offset:2048
	ds_read_b128 v[176:179], v154 offset:3072
	s_add_u32 s30, s30, 0x80000
	s_addc_u32 s31, s31, 0
	s_add_u32 s100, s30, 0xfff80080
	s_addc_u32 s101, s31, -1
	s_mov_b32 m0, s42
	ds_read_b128 v[180:183], v222 offset:32768
	ds_read_b128 v[184:187], v222 offset:33792
	ds_read_b128 v[188:191], v222 offset:34816
	ds_read_b128 v[192:195], v222 offset:35840
	ds_read_b128 v[196:199], v222 offset:36864
	ds_read_b128 v[200:203], v222 offset:37888
	ds_read_b128 v[204:207], v222 offset:38912
	ds_read_b128 v[208:211], v222 offset:39936
	global_load_lds_dwordx4 v146, s[30:31]
	s_mov_b32 m0, s43
	s_nop 0
	global_load_lds_dwordx4 v150, s[30:31]
	s_waitcnt vmcnt(8)
	s_waitcnt lgkmcnt(0)
	s_barrier
	s_setprio 1
	s_waitcnt lgkmcnt(0)
	v_mfma_f32_16x16x32_bf16 v[126:129], v[130:133], v[180:183], v[126:129]
	v_mfma_f32_16x16x32_bf16 v[122:125], v[138:141], v[180:183], v[122:125]
	v_mfma_f32_16x16x32_bf16 v[110:113], v[130:133], v[188:191], v[110:113]
	v_mfma_f32_16x16x32_bf16 v[106:109], v[138:141], v[188:191], v[106:109]
	v_mfma_f32_16x16x32_bf16 v[94:97], v[130:133], v[196:199], v[94:97]
	v_mfma_f32_16x16x32_bf16 v[90:93], v[138:141], v[196:199], v[90:93]
	v_mfma_f32_16x16x32_bf16 v[78:81], v[130:133], v[204:207], v[78:81]
	v_mfma_f32_16x16x32_bf16 v[74:77], v[138:141], v[204:207], v[74:77]
	v_mfma_f32_16x16x32_bf16 v[126:129], v[134:137], v[184:187], v[126:129]
	v_mfma_f32_16x16x32_bf16 v[122:125], v[142:145], v[184:187], v[122:125]
	v_mfma_f32_16x16x32_bf16 v[110:113], v[134:137], v[192:195], v[110:113]
	v_mfma_f32_16x16x32_bf16 v[106:109], v[142:145], v[192:195], v[106:109]
	v_mfma_f32_16x16x32_bf16 v[94:97], v[134:137], v[200:203], v[94:97]
	v_mfma_f32_16x16x32_bf16 v[90:93], v[142:145], v[200:203], v[90:93]
	v_mfma_f32_16x16x32_bf16 v[78:81], v[134:137], v[208:211], v[78:81]
	v_mfma_f32_16x16x32_bf16 v[74:77], v[142:145], v[208:211], v[74:77]
	s_setprio 0
	s_setprio 1
	v_mfma_f32_16x16x32_bf16 v[118:121], v[164:167], v[180:183], v[118:121]
	v_mfma_f32_16x16x32_bf16 v[114:117], v[172:175], v[180:183], v[114:117]
	v_mfma_f32_16x16x32_bf16 v[102:105], v[164:167], v[188:191], v[102:105]
	v_mfma_f32_16x16x32_bf16 v[98:101], v[172:175], v[188:191], v[98:101]
	v_mfma_f32_16x16x32_bf16 v[86:89], v[164:167], v[196:199], v[86:89]
	v_mfma_f32_16x16x32_bf16 v[82:85], v[172:175], v[196:199], v[82:85]
	v_mfma_f32_16x16x32_bf16 v[70:73], v[164:167], v[204:207], v[70:73]
	v_mfma_f32_16x16x32_bf16 v[66:69], v[172:175], v[204:207], v[66:69]
	v_mfma_f32_16x16x32_bf16 v[118:121], v[168:171], v[184:187], v[118:121]
	v_mfma_f32_16x16x32_bf16 v[114:117], v[176:179], v[184:187], v[114:117]
	v_mfma_f32_16x16x32_bf16 v[102:105], v[168:171], v[192:195], v[102:105]
	v_mfma_f32_16x16x32_bf16 v[98:101], v[176:179], v[192:195], v[98:101]
	v_mfma_f32_16x16x32_bf16 v[86:89], v[168:171], v[200:203], v[86:89]
	v_mfma_f32_16x16x32_bf16 v[82:85], v[176:179], v[200:203], v[82:85]
	v_mfma_f32_16x16x32_bf16 v[70:73], v[168:171], v[208:211], v[70:73]
	v_mfma_f32_16x16x32_bf16 v[66:69], v[176:179], v[208:211], v[66:69]
	s_setprio 0
	s_barrier
	s_add_i32 s30, s68, s39
	s_mov_b32 m0, s30
	ds_read_b128 v[180:183], v222 offset:49152
	ds_read_b128 v[184:187], v222 offset:50176
	ds_read_b128 v[188:191], v222 offset:51200
	ds_read_b128 v[192:195], v222 offset:52224
	ds_read_b128 v[196:199], v222 offset:53248
	ds_read_b128 v[200:203], v222 offset:54272
	ds_read_b128 v[204:207], v222 offset:55296
	ds_read_b128 v[208:211], v222 offset:56320
	s_add_u32 s98, s28, 0x80
	s_addc_u32 s99, s29, 0
	global_load_lds_dwordx4 v148, s[98:99]
	s_add_i32 m0, s30, 0x2000
	s_add_u32 s28, s28, 0x80080
	s_addc_u32 s29, s29, 0
	s_add_i32 s30, s69, s39
	global_load_lds_dwordx4 v152, s[98:99]
	s_mov_b32 m0, s30
	s_nop 0
	global_load_lds_dwordx4 v148, s[28:29]
	s_add_i32 m0, s30, 0x2000
	s_nop 0
	global_load_lds_dwordx4 v152, s[28:29]
	s_mov_b32 m0, s87
	s_nop 0
	global_load_lds_dwordx4 v146, s[100:101]
	s_mov_b32 m0, s92
	s_nop 0
	global_load_lds_dwordx4 v150, s[100:101]
	s_waitcnt vmcnt(8)
	s_waitcnt lgkmcnt(0)
	s_barrier
	s_setprio 1
	s_waitcnt lgkmcnt(0)
	v_mfma_f32_16x16x32_bf16 v[62:65], v[130:133], v[180:183], v[62:65]
	v_mfma_f32_16x16x32_bf16 v[58:61], v[138:141], v[180:183], v[58:61]
	v_mfma_f32_16x16x32_bf16 v[46:49], v[130:133], v[188:191], v[46:49]
	v_mfma_f32_16x16x32_bf16 v[42:45], v[138:141], v[188:191], v[42:45]
	v_mfma_f32_16x16x32_bf16 v[30:33], v[130:133], v[196:199], v[30:33]
	v_mfma_f32_16x16x32_bf16 v[26:29], v[138:141], v[196:199], v[26:29]
	v_mfma_f32_16x16x32_bf16 v[14:17], v[130:133], v[204:207], v[14:17]
	v_mfma_f32_16x16x32_bf16 v[10:13], v[138:141], v[204:207], v[10:13]
	v_mfma_f32_16x16x32_bf16 v[62:65], v[134:137], v[184:187], v[62:65]
	v_mfma_f32_16x16x32_bf16 v[58:61], v[142:145], v[184:187], v[58:61]
	v_mfma_f32_16x16x32_bf16 v[46:49], v[134:137], v[192:195], v[46:49]
	v_mfma_f32_16x16x32_bf16 v[42:45], v[142:145], v[192:195], v[42:45]
	v_mfma_f32_16x16x32_bf16 v[30:33], v[134:137], v[200:203], v[30:33]
	v_mfma_f32_16x16x32_bf16 v[26:29], v[142:145], v[200:203], v[26:29]
	v_mfma_f32_16x16x32_bf16 v[14:17], v[134:137], v[208:211], v[14:17]
	v_mfma_f32_16x16x32_bf16 v[10:13], v[142:145], v[208:211], v[10:13]
	s_setprio 0
	s_setprio 1
	v_mfma_f32_16x16x32_bf16 v[54:57], v[164:167], v[180:183], v[54:57]
	v_mfma_f32_16x16x32_bf16 v[50:53], v[172:175], v[180:183], v[50:53]
	v_mfma_f32_16x16x32_bf16 v[38:41], v[164:167], v[188:191], v[38:41]
	v_mfma_f32_16x16x32_bf16 v[34:37], v[172:175], v[188:191], v[34:37]
	v_mfma_f32_16x16x32_bf16 v[22:25], v[164:167], v[196:199], v[22:25]
	v_mfma_f32_16x16x32_bf16 v[18:21], v[172:175], v[196:199], v[18:21]
	v_mfma_f32_16x16x32_bf16 v[6:9], v[164:167], v[204:207], v[6:9]
	v_mfma_f32_16x16x32_bf16 v[2:5], v[172:175], v[204:207], v[2:5]
	v_mfma_f32_16x16x32_bf16 v[54:57], v[168:171], v[184:187], v[54:57]
	v_mfma_f32_16x16x32_bf16 v[50:53], v[176:179], v[184:187], v[50:53]
	v_mfma_f32_16x16x32_bf16 v[38:41], v[168:171], v[192:195], v[38:41]
	v_mfma_f32_16x16x32_bf16 v[34:37], v[176:179], v[192:195], v[34:37]
	v_mfma_f32_16x16x32_bf16 v[22:25], v[168:171], v[200:203], v[22:25]
	v_mfma_f32_16x16x32_bf16 v[18:21], v[176:179], v[200:203], v[18:21]
	v_mfma_f32_16x16x32_bf16 v[6:9], v[168:171], v[208:211], v[6:9]
	v_mfma_f32_16x16x32_bf16 v[2:5], v[176:179], v[208:211], v[2:5]
	s_setprio 0
	s_barrier
	s_add_i32 s35, s35, 2
	s_add_u32 s6, s6, 0x100
	s_addc_u32 s7, s7, 0
	s_add_u32 s33, s33, 0x100
	s_addc_u32 s34, s34, 0
	s_cmp_gt_u32 s35, 29
	s_cbranch_scc0 .LBB0_150
	s_and_b64 vcc, exec, s[88:89]
	s_cbranch_vccz .LBB0_153
	s_barrier

.LBB0_988:
	ds_read_b128 v[152:155], v148
	ds_read_b128 v[156:159], v148 offset:1024
	ds_read_b128 v[160:163], v148 offset:2048
	ds_read_b128 v[164:167], v148 offset:3072
	ds_read_b128 v[168:171], v149
	ds_read_b128 v[172:175], v149 offset:1024
	ds_read_b128 v[176:179], v149 offset:2048
	ds_read_b128 v[180:183], v149 offset:3072
	s_add_u32 s34, s30, 0xfff80080
	s_addc_u32 s35, s31, -1
	s_cmp_eq_u32 s59, 28
	s_cselect_b32 s37, s23, s35
	s_cselect_b32 s36, s55, s34
	s_cselect_b32 s35, s21, s58
	s_cselect_b32 s34, s56, s57
	s_add_i32 m0, s29, 0xc000
	ds_read_b128 v[184:187], v150
	ds_read_b128 v[188:191], v150 offset:1024
	ds_read_b128 v[192:195], v150 offset:2048
	ds_read_b128 v[196:199], v150 offset:3072
	ds_read_b128 v[200:203], v150 offset:4096
	ds_read_b128 v[204:207], v150 offset:5120
	ds_read_b128 v[208:211], v150 offset:6144
	ds_read_b128 v[212:215], v150 offset:7168
	global_load_lds_dwordx4 v138, s[30:31]
	s_add_i32 m0, s29, 0xe000
	s_nop 0
	global_load_lds_dwordx4 v140, s[30:31]
	s_waitcnt vmcnt(8)
	s_waitcnt lgkmcnt(0)
	s_barrier
	s_setprio 1
	s_waitcnt lgkmcnt(0)
	v_mfma_f32_16x16x32_bf16 v[126:129], v[152:155], v[184:187], v[126:129]
	v_mfma_f32_16x16x32_bf16 v[122:125], v[160:163], v[184:187], v[122:125]
	v_mfma_f32_16x16x32_bf16 v[118:121], v[152:155], v[192:195], v[118:121]
	v_mfma_f32_16x16x32_bf16 v[110:113], v[160:163], v[192:195], v[110:113]
	v_mfma_f32_16x16x32_bf16 v[102:105], v[152:155], v[200:203], v[102:105]
	v_mfma_f32_16x16x32_bf16 v[94:97], v[160:163], v[200:203], v[94:97]
	v_mfma_f32_16x16x32_bf16 v[86:89], v[152:155], v[208:211], v[86:89]
	v_mfma_f32_16x16x32_bf16 v[78:81], v[160:163], v[208:211], v[78:81]
	v_mfma_f32_16x16x32_bf16 v[126:129], v[156:159], v[188:191], v[126:129]
	v_mfma_f32_16x16x32_bf16 v[122:125], v[164:167], v[188:191], v[122:125]
	v_mfma_f32_16x16x32_bf16 v[118:121], v[156:159], v[196:199], v[118:121]
	v_mfma_f32_16x16x32_bf16 v[110:113], v[164:167], v[196:199], v[110:113]
	v_mfma_f32_16x16x32_bf16 v[102:105], v[156:159], v[204:207], v[102:105]
	v_mfma_f32_16x16x32_bf16 v[94:97], v[164:167], v[204:207], v[94:97]
	v_mfma_f32_16x16x32_bf16 v[86:89], v[156:159], v[212:215], v[86:89]
	v_mfma_f32_16x16x32_bf16 v[78:81], v[164:167], v[212:215], v[78:81]
	s_setprio 0
	s_setprio 1
	v_mfma_f32_16x16x32_bf16 v[114:117], v[168:171], v[184:187], v[114:117]
	v_mfma_f32_16x16x32_bf16 v[106:109], v[176:179], v[184:187], v[106:109]
	v_mfma_f32_16x16x32_bf16 v[98:101], v[168:171], v[192:195], v[98:101]
	v_mfma_f32_16x16x32_bf16 v[90:93], v[176:179], v[192:195], v[90:93]
	v_mfma_f32_16x16x32_bf16 v[82:85], v[168:171], v[200:203], v[82:85]
	v_mfma_f32_16x16x32_bf16 v[74:77], v[176:179], v[200:203], v[74:77]
	v_mfma_f32_16x16x32_bf16 v[70:73], v[168:171], v[208:211], v[70:73]
	v_mfma_f32_16x16x32_bf16 v[66:69], v[176:179], v[208:211], v[66:69]
	v_mfma_f32_16x16x32_bf16 v[114:117], v[172:175], v[188:191], v[114:117]
	v_mfma_f32_16x16x32_bf16 v[106:109], v[180:183], v[188:191], v[106:109]
	v_mfma_f32_16x16x32_bf16 v[98:101], v[172:175], v[196:199], v[98:101]
	v_mfma_f32_16x16x32_bf16 v[90:93], v[180:183], v[196:199], v[90:93]
	v_mfma_f32_16x16x32_bf16 v[82:85], v[172:175], v[204:207], v[82:85]
	v_mfma_f32_16x16x32_bf16 v[74:77], v[180:183], v[204:207], v[74:77]
	v_mfma_f32_16x16x32_bf16 v[70:73], v[172:175], v[212:215], v[70:73]
	v_mfma_f32_16x16x32_bf16 v[66:69], v[180:183], v[212:215], v[66:69]
	s_setprio 0
	s_barrier
	s_add_i32 s60, s48, s39
	s_mov_b32 m0, s60
	ds_read_b128 v[184:187], v150 offset:16384
	ds_read_b128 v[188:191], v150 offset:17408
	ds_read_b128 v[192:195], v150 offset:18432
	ds_read_b128 v[196:199], v150 offset:19456
	ds_read_b128 v[200:203], v150 offset:20480
	ds_read_b128 v[204:207], v150 offset:21504
	ds_read_b128 v[208:211], v150 offset:22528
	ds_read_b128 v[212:215], v150 offset:23552
	global_load_lds_dwordx4 v132, s[34:35]
	s_add_i32 m0, s60, 0x2000
	s_add_u32 s60, s34, 0x80000
	s_addc_u32 s61, s35, 0
	s_add_i32 s62, s49, s39
	global_load_lds_dwordx4 v136, s[34:35]
	s_mov_b32 m0, s62
	s_nop 0
	global_load_lds_dwordx4 v132, s[60:61]
	s_add_i32 m0, s62, 0x2000
	s_nop 0
	global_load_lds_dwordx4 v136, s[60:61]
	s_mov_b32 m0, s29
	s_nop 0
	global_load_lds_dwordx4 v130, s[36:37]
	s_mov_b32 m0, s41
	s_nop 0
	global_load_lds_dwordx4 v134, s[36:37]
	s_waitcnt vmcnt(8)
	s_waitcnt lgkmcnt(0)
	s_barrier
	s_setprio 1
	s_waitcnt lgkmcnt(0)
	v_mfma_f32_16x16x32_bf16 v[62:65], v[152:155], v[184:187], v[62:65]
	v_mfma_f32_16x16x32_bf16 v[58:61], v[160:163], v[184:187], v[58:61]
	v_mfma_f32_16x16x32_bf16 v[54:57], v[152:155], v[192:195], v[54:57]
	v_mfma_f32_16x16x32_bf16 v[46:49], v[160:163], v[192:195], v[46:49]
	v_mfma_f32_16x16x32_bf16 v[38:41], v[152:155], v[200:203], v[38:41]
	v_mfma_f32_16x16x32_bf16 v[30:33], v[160:163], v[200:203], v[30:33]
	v_mfma_f32_16x16x32_bf16 v[22:25], v[152:155], v[208:211], v[22:25]
	v_mfma_f32_16x16x32_bf16 v[14:17], v[160:163], v[208:211], v[14:17]
	v_mfma_f32_16x16x32_bf16 v[62:65], v[156:159], v[188:191], v[62:65]
	v_mfma_f32_16x16x32_bf16 v[58:61], v[164:167], v[188:191], v[58:61]
	v_mfma_f32_16x16x32_bf16 v[54:57], v[156:159], v[196:199], v[54:57]
	v_mfma_f32_16x16x32_bf16 v[46:49], v[164:167], v[196:199], v[46:49]
	v_mfma_f32_16x16x32_bf16 v[38:41], v[156:159], v[204:207], v[38:41]
	v_mfma_f32_16x16x32_bf16 v[30:33], v[164:167], v[204:207], v[30:33]
	v_mfma_f32_16x16x32_bf16 v[22:25], v[156:159], v[212:215], v[22:25]
	v_mfma_f32_16x16x32_bf16 v[14:17], v[164:167], v[212:215], v[14:17]
	s_setprio 0
	s_setprio 1
	v_mfma_f32_16x16x32_bf16 v[50:53], v[168:171], v[184:187], v[50:53]
	v_mfma_f32_16x16x32_bf16 v[42:45], v[176:179], v[184:187], v[42:45]
	v_mfma_f32_16x16x32_bf16 v[34:37], v[168:171], v[192:195], v[34:37]
	v_mfma_f32_16x16x32_bf16 v[26:29], v[176:179], v[192:195], v[26:29]
	v_mfma_f32_16x16x32_bf16 v[18:21], v[168:171], v[200:203], v[18:21]
	v_mfma_f32_16x16x32_bf16 v[10:13], v[176:179], v[200:203], v[10:13]
	v_mfma_f32_16x16x32_bf16 v[6:9], v[168:171], v[208:211], v[6:9]
	v_mfma_f32_16x16x32_bf16 v[2:5], v[176:179], v[208:211], v[2:5]
	v_mfma_f32_16x16x32_bf16 v[50:53], v[172:175], v[188:191], v[50:53]
	v_mfma_f32_16x16x32_bf16 v[42:45], v[180:183], v[188:191], v[42:45]
	v_mfma_f32_16x16x32_bf16 v[34:37], v[172:175], v[196:199], v[34:37]
	v_mfma_f32_16x16x32_bf16 v[26:29], v[180:183], v[196:199], v[26:29]
	v_mfma_f32_16x16x32_bf16 v[18:21], v[172:175], v[204:207], v[18:21]
	v_mfma_f32_16x16x32_bf16 v[10:13], v[180:183], v[204:207], v[10:13]
	v_mfma_f32_16x16x32_bf16 v[6:9], v[172:175], v[212:215], v[6:9]
	v_mfma_f32_16x16x32_bf16 v[2:5], v[180:183], v[212:215], v[2:5]
	s_setprio 0
	s_barrier
	s_add_i32 s60, 0, 0x18000
	v_add_u32_e32 v151, s60, v146
	s_add_i32 s61, 0, 0x1c000
	ds_read_b128 v[152:155], v151
	ds_read_b128 v[156:159], v151 offset:1024
	ds_read_b128 v[160:163], v151 offset:2048
	ds_read_b128 v[164:167], v151 offset:3072
	v_add_u32_e32 v151, s61, v146
	ds_read_b128 v[168:171], v151
	ds_read_b128 v[172:175], v151 offset:1024
	ds_read_b128 v[176:179], v151 offset:2048
	ds_read_b128 v[180:183], v151 offset:3072
	s_add_u32 s36, s36, 0x80000
	s_addc_u32 s37, s37, 0
	s_add_u32 s100, s36, 0xfff80080
	s_addc_u32 s101, s37, -1
	s_mov_b32 m0, s42
	ds_read_b128 v[184:187], v150 offset:32768
	ds_read_b128 v[188:191], v150 offset:33792
	ds_read_b128 v[192:195], v150 offset:34816
	ds_read_b128 v[196:199], v150 offset:35840
	ds_read_b128 v[200:203], v150 offset:36864
	ds_read_b128 v[204:207], v150 offset:37888
	ds_read_b128 v[208:211], v150 offset:38912
	ds_read_b128 v[212:215], v150 offset:39936
	global_load_lds_dwordx4 v130, s[36:37]
	s_mov_b32 m0, s43
	s_nop 0
	global_load_lds_dwordx4 v134, s[36:37]
	s_waitcnt vmcnt(8)
	s_waitcnt lgkmcnt(0)
	s_barrier
	s_setprio 1
	s_waitcnt lgkmcnt(0)
	v_mfma_f32_16x16x32_bf16 v[126:129], v[152:155], v[184:187], v[126:129]
	v_mfma_f32_16x16x32_bf16 v[122:125], v[160:163], v[184:187], v[122:125]
	v_mfma_f32_16x16x32_bf16 v[118:121], v[152:155], v[192:195], v[118:121]
	v_mfma_f32_16x16x32_bf16 v[110:113], v[160:163], v[192:195], v[110:113]
	v_mfma_f32_16x16x32_bf16 v[102:105], v[152:155], v[200:203], v[102:105]
	v_mfma_f32_16x16x32_bf16 v[94:97], v[160:163], v[200:203], v[94:97]
	v_mfma_f32_16x16x32_bf16 v[86:89], v[152:155], v[208:211], v[86:89]
	v_mfma_f32_16x16x32_bf16 v[78:81], v[160:163], v[208:211], v[78:81]
	v_mfma_f32_16x16x32_bf16 v[126:129], v[156:159], v[188:191], v[126:129]
	v_mfma_f32_16x16x32_bf16 v[122:125], v[164:167], v[188:191], v[122:125]
	v_mfma_f32_16x16x32_bf16 v[118:121], v[156:159], v[196:199], v[118:121]
	v_mfma_f32_16x16x32_bf16 v[110:113], v[164:167], v[196:199], v[110:113]
	v_mfma_f32_16x16x32_bf16 v[102:105], v[156:159], v[204:207], v[102:105]
	v_mfma_f32_16x16x32_bf16 v[94:97], v[164:167], v[204:207], v[94:97]
	v_mfma_f32_16x16x32_bf16 v[86:89], v[156:159], v[212:215], v[86:89]
	v_mfma_f32_16x16x32_bf16 v[78:81], v[164:167], v[212:215], v[78:81]
	s_setprio 0
	s_setprio 1
	v_mfma_f32_16x16x32_bf16 v[114:117], v[168:171], v[184:187], v[114:117]
	v_mfma_f32_16x16x32_bf16 v[106:109], v[176:179], v[184:187], v[106:109]
	v_mfma_f32_16x16x32_bf16 v[98:101], v[168:171], v[192:195], v[98:101]
	v_mfma_f32_16x16x32_bf16 v[90:93], v[176:179], v[192:195], v[90:93]
	v_mfma_f32_16x16x32_bf16 v[82:85], v[168:171], v[200:203], v[82:85]
	v_mfma_f32_16x16x32_bf16 v[74:77], v[176:179], v[200:203], v[74:77]
	v_mfma_f32_16x16x32_bf16 v[70:73], v[168:171], v[208:211], v[70:73]
	v_mfma_f32_16x16x32_bf16 v[66:69], v[176:179], v[208:211], v[66:69]
	v_mfma_f32_16x16x32_bf16 v[114:117], v[172:175], v[188:191], v[114:117]
	v_mfma_f32_16x16x32_bf16 v[106:109], v[180:183], v[188:191], v[106:109]
	v_mfma_f32_16x16x32_bf16 v[98:101], v[172:175], v[196:199], v[98:101]
	v_mfma_f32_16x16x32_bf16 v[90:93], v[180:183], v[196:199], v[90:93]
	v_mfma_f32_16x16x32_bf16 v[82:85], v[172:175], v[204:207], v[82:85]
	v_mfma_f32_16x16x32_bf16 v[74:77], v[180:183], v[204:207], v[74:77]
	v_mfma_f32_16x16x32_bf16 v[70:73], v[172:175], v[212:215], v[70:73]
	v_mfma_f32_16x16x32_bf16 v[66:69], v[180:183], v[212:215], v[66:69]
	s_setprio 0
	s_barrier
	s_add_i32 s36, s60, s39
	s_mov_b32 m0, s36
	ds_read_b128 v[184:187], v150 offset:49152
	ds_read_b128 v[188:191], v150 offset:50176
	ds_read_b128 v[192:195], v150 offset:51200
	ds_read_b128 v[196:199], v150 offset:52224
	ds_read_b128 v[200:203], v150 offset:53248
	ds_read_b128 v[204:207], v150 offset:54272
	ds_read_b128 v[208:211], v150 offset:55296
	ds_read_b128 v[212:215], v150 offset:56320
	s_add_u32 s98, s34, 0x80
	s_addc_u32 s99, s35, 0
	global_load_lds_dwordx4 v132, s[98:99]
	s_add_i32 m0, s36, 0x2000
	s_add_u32 s34, s34, 0x80080
	s_addc_u32 s35, s35, 0
	s_add_i32 s36, s61, s39
	global_load_lds_dwordx4 v136, s[98:99]
	s_mov_b32 m0, s36
	s_nop 0
	global_load_lds_dwordx4 v132, s[34:35]
	s_add_i32 m0, s36, 0x2000
	s_nop 0
	global_load_lds_dwordx4 v136, s[34:35]
	s_mov_b32 m0, s46
	s_nop 0
	global_load_lds_dwordx4 v130, s[100:101]
	s_mov_b32 m0, s47
	s_nop 0
	global_load_lds_dwordx4 v134, s[100:101]
	s_waitcnt vmcnt(8)
	s_waitcnt lgkmcnt(0)
	s_barrier
	s_setprio 1
	s_waitcnt lgkmcnt(0)
	v_mfma_f32_16x16x32_bf16 v[62:65], v[152:155], v[184:187], v[62:65]
	v_mfma_f32_16x16x32_bf16 v[58:61], v[160:163], v[184:187], v[58:61]
	v_mfma_f32_16x16x32_bf16 v[54:57], v[152:155], v[192:195], v[54:57]
	v_mfma_f32_16x16x32_bf16 v[46:49], v[160:163], v[192:195], v[46:49]
	v_mfma_f32_16x16x32_bf16 v[38:41], v[152:155], v[200:203], v[38:41]
	v_mfma_f32_16x16x32_bf16 v[30:33], v[160:163], v[200:203], v[30:33]
	v_mfma_f32_16x16x32_bf16 v[22:25], v[152:155], v[208:211], v[22:25]
	v_mfma_f32_16x16x32_bf16 v[14:17], v[160:163], v[208:211], v[14:17]
	v_mfma_f32_16x16x32_bf16 v[62:65], v[156:159], v[188:191], v[62:65]
	v_mfma_f32_16x16x32_bf16 v[58:61], v[164:167], v[188:191], v[58:61]
	v_mfma_f32_16x16x32_bf16 v[54:57], v[156:159], v[196:199], v[54:57]
	v_mfma_f32_16x16x32_bf16 v[46:49], v[164:167], v[196:199], v[46:49]
	v_mfma_f32_16x16x32_bf16 v[38:41], v[156:159], v[204:207], v[38:41]
	v_mfma_f32_16x16x32_bf16 v[30:33], v[164:167], v[204:207], v[30:33]
	v_mfma_f32_16x16x32_bf16 v[22:25], v[156:159], v[212:215], v[22:25]
	v_mfma_f32_16x16x32_bf16 v[14:17], v[164:167], v[212:215], v[14:17]
	s_setprio 0
	s_setprio 1
	v_mfma_f32_16x16x32_bf16 v[50:53], v[168:171], v[184:187], v[50:53]
	v_mfma_f32_16x16x32_bf16 v[42:45], v[176:179], v[184:187], v[42:45]
	v_mfma_f32_16x16x32_bf16 v[34:37], v[168:171], v[192:195], v[34:37]
	v_mfma_f32_16x16x32_bf16 v[26:29], v[176:179], v[192:195], v[26:29]
	v_mfma_f32_16x16x32_bf16 v[18:21], v[168:171], v[200:203], v[18:21]
	v_mfma_f32_16x16x32_bf16 v[10:13], v[176:179], v[200:203], v[10:13]
	v_mfma_f32_16x16x32_bf16 v[6:9], v[168:171], v[208:211], v[6:9]
	v_mfma_f32_16x16x32_bf16 v[2:5], v[176:179], v[208:211], v[2:5]
	v_mfma_f32_16x16x32_bf16 v[50:53], v[172:175], v[188:191], v[50:53]
	v_mfma_f32_16x16x32_bf16 v[42:45], v[180:183], v[188:191], v[42:45]
	v_mfma_f32_16x16x32_bf16 v[34:37], v[172:175], v[196:199], v[34:37]
	v_mfma_f32_16x16x32_bf16 v[26:29], v[180:183], v[196:199], v[26:29]
	v_mfma_f32_16x16x32_bf16 v[18:21], v[172:175], v[204:207], v[18:21]
	v_mfma_f32_16x16x32_bf16 v[10:13], v[180:183], v[204:207], v[10:13]
	v_mfma_f32_16x16x32_bf16 v[6:9], v[172:175], v[212:215], v[6:9]
	v_mfma_f32_16x16x32_bf16 v[2:5], v[180:183], v[212:215], v[2:5]
	s_setprio 0
	s_barrier
	s_add_i32 s59, s59, 2
	s_add_u32 s30, s30, 0x100
	s_addc_u32 s31, s31, 0
	s_add_u32 s57, s57, 0x100
	s_addc_u32 s58, s58, 0
	s_cmp_gt_u32 s59, 29
	s_cbranch_scc0 .LBB0_988
	s_and_b64 vcc, exec, s[12:13]
	s_cbranch_vccz .LBB0_991
	s_barrier

.LBB0_1222:
	ds_read_b128 v[152:155], v148
	ds_read_b128 v[156:159], v148 offset:1024
	ds_read_b128 v[160:163], v148 offset:2048
	ds_read_b128 v[164:167], v148 offset:3072
	ds_read_b128 v[168:171], v149
	ds_read_b128 v[172:175], v149 offset:1024
	ds_read_b128 v[176:179], v149 offset:2048
	ds_read_b128 v[180:183], v149 offset:3072
	s_add_u32 s26, s24, 0xffea0080
	s_addc_u32 s27, s25, -1
	s_cmpk_eq_i32 s55, 0x54
	s_cselect_b32 s29, s3, s27
	s_cselect_b32 s28, s2, s26
	s_cselect_b32 s27, s23, s54
	s_cselect_b32 s26, s22, s53
	s_add_i32 m0, s35, 0xc000
	ds_read_b128 v[184:187], v150
	ds_read_b128 v[188:191], v150 offset:1024
	ds_read_b128 v[192:195], v150 offset:2048
	ds_read_b128 v[196:199], v150 offset:3072
	ds_read_b128 v[200:203], v150 offset:4096
	ds_read_b128 v[204:207], v150 offset:5120
	ds_read_b128 v[208:211], v150 offset:6144
	ds_read_b128 v[212:215], v150 offset:7168
	global_load_lds_dwordx4 v138, s[24:25]
	s_add_i32 m0, s35, 0xe000
	s_nop 0
	global_load_lds_dwordx4 v140, s[24:25]
	s_waitcnt vmcnt(8)
	s_waitcnt lgkmcnt(0)
	s_barrier
	s_setprio 1
	s_waitcnt lgkmcnt(0)
	v_mfma_f32_16x16x32_bf16 v[126:129], v[152:155], v[184:187], v[126:129]
	v_mfma_f32_16x16x32_bf16 v[122:125], v[160:163], v[184:187], v[122:125]
	v_mfma_f32_16x16x32_bf16 v[118:121], v[152:155], v[192:195], v[118:121]
	v_mfma_f32_16x16x32_bf16 v[110:113], v[160:163], v[192:195], v[110:113]
	v_mfma_f32_16x16x32_bf16 v[102:105], v[152:155], v[200:203], v[102:105]
	v_mfma_f32_16x16x32_bf16 v[94:97], v[160:163], v[200:203], v[94:97]
	v_mfma_f32_16x16x32_bf16 v[86:89], v[152:155], v[208:211], v[86:89]
	v_mfma_f32_16x16x32_bf16 v[78:81], v[160:163], v[208:211], v[78:81]
	v_mfma_f32_16x16x32_bf16 v[126:129], v[156:159], v[188:191], v[126:129]
	v_mfma_f32_16x16x32_bf16 v[122:125], v[164:167], v[188:191], v[122:125]
	v_mfma_f32_16x16x32_bf16 v[118:121], v[156:159], v[196:199], v[118:121]
	v_mfma_f32_16x16x32_bf16 v[110:113], v[164:167], v[196:199], v[110:113]
	v_mfma_f32_16x16x32_bf16 v[102:105], v[156:159], v[204:207], v[102:105]
	v_mfma_f32_16x16x32_bf16 v[94:97], v[164:167], v[204:207], v[94:97]
	v_mfma_f32_16x16x32_bf16 v[86:89], v[156:159], v[212:215], v[86:89]
	v_mfma_f32_16x16x32_bf16 v[78:81], v[164:167], v[212:215], v[78:81]
	s_setprio 0
	s_setprio 1
	v_mfma_f32_16x16x32_bf16 v[114:117], v[168:171], v[184:187], v[114:117]
	v_mfma_f32_16x16x32_bf16 v[106:109], v[176:179], v[184:187], v[106:109]
	v_mfma_f32_16x16x32_bf16 v[98:101], v[168:171], v[192:195], v[98:101]
	v_mfma_f32_16x16x32_bf16 v[90:93], v[176:179], v[192:195], v[90:93]
	v_mfma_f32_16x16x32_bf16 v[82:85], v[168:171], v[200:203], v[82:85]
	v_mfma_f32_16x16x32_bf16 v[74:77], v[176:179], v[200:203], v[74:77]
	v_mfma_f32_16x16x32_bf16 v[70:73], v[168:171], v[208:211], v[70:73]
	v_mfma_f32_16x16x32_bf16 v[66:69], v[176:179], v[208:211], v[66:69]
	v_mfma_f32_16x16x32_bf16 v[114:117], v[172:175], v[188:191], v[114:117]
	v_mfma_f32_16x16x32_bf16 v[106:109], v[180:183], v[188:191], v[106:109]
	v_mfma_f32_16x16x32_bf16 v[98:101], v[172:175], v[196:199], v[98:101]
	v_mfma_f32_16x16x32_bf16 v[90:93], v[180:183], v[196:199], v[90:93]
	v_mfma_f32_16x16x32_bf16 v[82:85], v[172:175], v[204:207], v[82:85]
	v_mfma_f32_16x16x32_bf16 v[74:77], v[180:183], v[204:207], v[74:77]
	v_mfma_f32_16x16x32_bf16 v[70:73], v[172:175], v[212:215], v[70:73]
	v_mfma_f32_16x16x32_bf16 v[66:69], v[180:183], v[212:215], v[66:69]
	s_setprio 0
	s_barrier
	s_add_i32 s56, s43, s33
	s_mov_b32 m0, s56
	ds_read_b128 v[184:187], v150 offset:16384
	ds_read_b128 v[188:191], v150 offset:17408
	ds_read_b128 v[192:195], v150 offset:18432
	ds_read_b128 v[196:199], v150 offset:19456
	ds_read_b128 v[200:203], v150 offset:20480
	ds_read_b128 v[204:207], v150 offset:21504
	ds_read_b128 v[208:211], v150 offset:22528
	ds_read_b128 v[212:215], v150 offset:23552
	global_load_lds_dwordx4 v132, s[26:27]
	s_add_i32 m0, s56, 0x2000
	s_add_u32 s56, s26, 0x160000
	s_addc_u32 s57, s27, 0
	s_add_i32 s58, s44, s33
	global_load_lds_dwordx4 v136, s[26:27]
	s_mov_b32 m0, s58
	s_nop 0
	global_load_lds_dwordx4 v132, s[56:57]
	s_add_i32 m0, s58, 0x2000
	s_nop 0
	global_load_lds_dwordx4 v136, s[56:57]
	s_mov_b32 m0, s35
	s_nop 0
	global_load_lds_dwordx4 v130, s[28:29]
	s_mov_b32 m0, s36
	s_nop 0
	global_load_lds_dwordx4 v134, s[28:29]
	s_waitcnt vmcnt(8)
	s_waitcnt lgkmcnt(0)
	s_barrier
	s_setprio 1
	s_waitcnt lgkmcnt(0)
	v_mfma_f32_16x16x32_bf16 v[62:65], v[152:155], v[184:187], v[62:65]
	v_mfma_f32_16x16x32_bf16 v[58:61], v[160:163], v[184:187], v[58:61]
	v_mfma_f32_16x16x32_bf16 v[54:57], v[152:155], v[192:195], v[54:57]
	v_mfma_f32_16x16x32_bf16 v[46:49], v[160:163], v[192:195], v[46:49]
	v_mfma_f32_16x16x32_bf16 v[38:41], v[152:155], v[200:203], v[38:41]
	v_mfma_f32_16x16x32_bf16 v[30:33], v[160:163], v[200:203], v[30:33]
	v_mfma_f32_16x16x32_bf16 v[22:25], v[152:155], v[208:211], v[22:25]
	v_mfma_f32_16x16x32_bf16 v[14:17], v[160:163], v[208:211], v[14:17]
	v_mfma_f32_16x16x32_bf16 v[62:65], v[156:159], v[188:191], v[62:65]
	v_mfma_f32_16x16x32_bf16 v[58:61], v[164:167], v[188:191], v[58:61]
	v_mfma_f32_16x16x32_bf16 v[54:57], v[156:159], v[196:199], v[54:57]
	v_mfma_f32_16x16x32_bf16 v[46:49], v[164:167], v[196:199], v[46:49]
	v_mfma_f32_16x16x32_bf16 v[38:41], v[156:159], v[204:207], v[38:41]
	v_mfma_f32_16x16x32_bf16 v[30:33], v[164:167], v[204:207], v[30:33]
	v_mfma_f32_16x16x32_bf16 v[22:25], v[156:159], v[212:215], v[22:25]
	v_mfma_f32_16x16x32_bf16 v[14:17], v[164:167], v[212:215], v[14:17]
	s_setprio 0
	s_setprio 1
	v_mfma_f32_16x16x32_bf16 v[50:53], v[168:171], v[184:187], v[50:53]
	v_mfma_f32_16x16x32_bf16 v[42:45], v[176:179], v[184:187], v[42:45]
	v_mfma_f32_16x16x32_bf16 v[34:37], v[168:171], v[192:195], v[34:37]
	v_mfma_f32_16x16x32_bf16 v[26:29], v[176:179], v[192:195], v[26:29]
	v_mfma_f32_16x16x32_bf16 v[18:21], v[168:171], v[200:203], v[18:21]
	v_mfma_f32_16x16x32_bf16 v[10:13], v[176:179], v[200:203], v[10:13]
	v_mfma_f32_16x16x32_bf16 v[6:9], v[168:171], v[208:211], v[6:9]
	v_mfma_f32_16x16x32_bf16 v[2:5], v[176:179], v[208:211], v[2:5]
	v_mfma_f32_16x16x32_bf16 v[50:53], v[172:175], v[188:191], v[50:53]
	v_mfma_f32_16x16x32_bf16 v[42:45], v[180:183], v[188:191], v[42:45]
	v_mfma_f32_16x16x32_bf16 v[34:37], v[172:175], v[196:199], v[34:37]
	v_mfma_f32_16x16x32_bf16 v[26:29], v[180:183], v[196:199], v[26:29]
	v_mfma_f32_16x16x32_bf16 v[18:21], v[172:175], v[204:207], v[18:21]
	v_mfma_f32_16x16x32_bf16 v[10:13], v[180:183], v[204:207], v[10:13]
	v_mfma_f32_16x16x32_bf16 v[6:9], v[172:175], v[212:215], v[6:9]
	v_mfma_f32_16x16x32_bf16 v[2:5], v[180:183], v[212:215], v[2:5]
	s_setprio 0
	s_barrier
	s_add_i32 s56, 0, 0x18000
	v_add_u32_e32 v151, s56, v146
	s_add_i32 s57, 0, 0x1c000
	ds_read_b128 v[152:155], v151
	ds_read_b128 v[156:159], v151 offset:1024
	ds_read_b128 v[160:163], v151 offset:2048
	ds_read_b128 v[164:167], v151 offset:3072
	v_add_u32_e32 v151, s57, v146
	ds_read_b128 v[168:171], v151
	ds_read_b128 v[172:175], v151 offset:1024
	ds_read_b128 v[176:179], v151 offset:2048
	ds_read_b128 v[180:183], v151 offset:3072
	s_add_u32 s28, s28, 0x160000
	s_addc_u32 s29, s29, 0
	s_add_u32 s100, s28, 0xffea0080
	s_addc_u32 s101, s29, -1
	s_mov_b32 m0, s37
	ds_read_b128 v[184:187], v150 offset:32768
	ds_read_b128 v[188:191], v150 offset:33792
	ds_read_b128 v[192:195], v150 offset:34816
	ds_read_b128 v[196:199], v150 offset:35840
	ds_read_b128 v[200:203], v150 offset:36864
	ds_read_b128 v[204:207], v150 offset:37888
	ds_read_b128 v[208:211], v150 offset:38912
	ds_read_b128 v[212:215], v150 offset:39936
	global_load_lds_dwordx4 v130, s[28:29]
	s_mov_b32 m0, s38
	s_nop 0
	global_load_lds_dwordx4 v134, s[28:29]
	s_waitcnt vmcnt(8)
	s_waitcnt lgkmcnt(0)
	s_barrier
	s_setprio 1
	s_waitcnt lgkmcnt(0)
	v_mfma_f32_16x16x32_bf16 v[126:129], v[152:155], v[184:187], v[126:129]
	v_mfma_f32_16x16x32_bf16 v[122:125], v[160:163], v[184:187], v[122:125]
	v_mfma_f32_16x16x32_bf16 v[118:121], v[152:155], v[192:195], v[118:121]
	v_mfma_f32_16x16x32_bf16 v[110:113], v[160:163], v[192:195], v[110:113]
	v_mfma_f32_16x16x32_bf16 v[102:105], v[152:155], v[200:203], v[102:105]
	v_mfma_f32_16x16x32_bf16 v[94:97], v[160:163], v[200:203], v[94:97]
	v_mfma_f32_16x16x32_bf16 v[86:89], v[152:155], v[208:211], v[86:89]
	v_mfma_f32_16x16x32_bf16 v[78:81], v[160:163], v[208:211], v[78:81]
	v_mfma_f32_16x16x32_bf16 v[126:129], v[156:159], v[188:191], v[126:129]
	v_mfma_f32_16x16x32_bf16 v[122:125], v[164:167], v[188:191], v[122:125]
	v_mfma_f32_16x16x32_bf16 v[118:121], v[156:159], v[196:199], v[118:121]
	v_mfma_f32_16x16x32_bf16 v[110:113], v[164:167], v[196:199], v[110:113]
	v_mfma_f32_16x16x32_bf16 v[102:105], v[156:159], v[204:207], v[102:105]
	v_mfma_f32_16x16x32_bf16 v[94:97], v[164:167], v[204:207], v[94:97]
	v_mfma_f32_16x16x32_bf16 v[86:89], v[156:159], v[212:215], v[86:89]
	v_mfma_f32_16x16x32_bf16 v[78:81], v[164:167], v[212:215], v[78:81]
	s_setprio 0
	s_setprio 1
	v_mfma_f32_16x16x32_bf16 v[114:117], v[168:171], v[184:187], v[114:117]
	v_mfma_f32_16x16x32_bf16 v[106:109], v[176:179], v[184:187], v[106:109]
	v_mfma_f32_16x16x32_bf16 v[98:101], v[168:171], v[192:195], v[98:101]
	v_mfma_f32_16x16x32_bf16 v[90:93], v[176:179], v[192:195], v[90:93]
	v_mfma_f32_16x16x32_bf16 v[82:85], v[168:171], v[200:203], v[82:85]
	v_mfma_f32_16x16x32_bf16 v[74:77], v[176:179], v[200:203], v[74:77]
	v_mfma_f32_16x16x32_bf16 v[70:73], v[168:171], v[208:211], v[70:73]
	v_mfma_f32_16x16x32_bf16 v[66:69], v[176:179], v[208:211], v[66:69]
	v_mfma_f32_16x16x32_bf16 v[114:117], v[172:175], v[188:191], v[114:117]
	v_mfma_f32_16x16x32_bf16 v[106:109], v[180:183], v[188:191], v[106:109]
	v_mfma_f32_16x16x32_bf16 v[98:101], v[172:175], v[196:199], v[98:101]
	v_mfma_f32_16x16x32_bf16 v[90:93], v[180:183], v[196:199], v[90:93]
	v_mfma_f32_16x16x32_bf16 v[82:85], v[172:175], v[204:207], v[82:85]
	v_mfma_f32_16x16x32_bf16 v[74:77], v[180:183], v[204:207], v[74:77]
	v_mfma_f32_16x16x32_bf16 v[70:73], v[172:175], v[212:215], v[70:73]
	v_mfma_f32_16x16x32_bf16 v[66:69], v[180:183], v[212:215], v[66:69]
	s_setprio 0
	s_barrier
	s_add_i32 s28, s56, s33
	s_mov_b32 m0, s28
	ds_read_b128 v[184:187], v150 offset:49152
	ds_read_b128 v[188:191], v150 offset:50176
	ds_read_b128 v[192:195], v150 offset:51200
	ds_read_b128 v[196:199], v150 offset:52224
	ds_read_b128 v[200:203], v150 offset:53248
	ds_read_b128 v[204:207], v150 offset:54272
	ds_read_b128 v[208:211], v150 offset:55296
	ds_read_b128 v[212:215], v150 offset:56320
	s_add_u32 s98, s26, 0x80
	s_addc_u32 s99, s27, 0
	global_load_lds_dwordx4 v132, s[98:99]
	s_add_i32 m0, s28, 0x2000
	s_add_u32 s26, s26, 0x160080
	s_addc_u32 s27, s27, 0
	s_add_i32 s28, s57, s33
	global_load_lds_dwordx4 v136, s[98:99]
	s_mov_b32 m0, s28
	s_nop 0
	global_load_lds_dwordx4 v132, s[26:27]
	s_add_i32 m0, s28, 0x2000
	s_nop 0
	global_load_lds_dwordx4 v136, s[26:27]
	s_mov_b32 m0, s41
	s_nop 0
	global_load_lds_dwordx4 v130, s[100:101]
	s_mov_b32 m0, s42
	s_nop 0
	global_load_lds_dwordx4 v134, s[100:101]
	s_waitcnt vmcnt(8)
	s_waitcnt lgkmcnt(0)
	s_barrier
	s_setprio 1
	s_waitcnt lgkmcnt(0)
	v_mfma_f32_16x16x32_bf16 v[62:65], v[152:155], v[184:187], v[62:65]
	v_mfma_f32_16x16x32_bf16 v[58:61], v[160:163], v[184:187], v[58:61]
	v_mfma_f32_16x16x32_bf16 v[54:57], v[152:155], v[192:195], v[54:57]
	v_mfma_f32_16x16x32_bf16 v[46:49], v[160:163], v[192:195], v[46:49]
	v_mfma_f32_16x16x32_bf16 v[38:41], v[152:155], v[200:203], v[38:41]
	v_mfma_f32_16x16x32_bf16 v[30:33], v[160:163], v[200:203], v[30:33]
	v_mfma_f32_16x16x32_bf16 v[22:25], v[152:155], v[208:211], v[22:25]
	v_mfma_f32_16x16x32_bf16 v[14:17], v[160:163], v[208:211], v[14:17]
	v_mfma_f32_16x16x32_bf16 v[62:65], v[156:159], v[188:191], v[62:65]
	v_mfma_f32_16x16x32_bf16 v[58:61], v[164:167], v[188:191], v[58:61]
	v_mfma_f32_16x16x32_bf16 v[54:57], v[156:159], v[196:199], v[54:57]
	v_mfma_f32_16x16x32_bf16 v[46:49], v[164:167], v[196:199], v[46:49]
	v_mfma_f32_16x16x32_bf16 v[38:41], v[156:159], v[204:207], v[38:41]
	v_mfma_f32_16x16x32_bf16 v[30:33], v[164:167], v[204:207], v[30:33]
	v_mfma_f32_16x16x32_bf16 v[22:25], v[156:159], v[212:215], v[22:25]
	v_mfma_f32_16x16x32_bf16 v[14:17], v[164:167], v[212:215], v[14:17]
	s_setprio 0
	s_setprio 1
	v_mfma_f32_16x16x32_bf16 v[50:53], v[168:171], v[184:187], v[50:53]
	v_mfma_f32_16x16x32_bf16 v[42:45], v[176:179], v[184:187], v[42:45]
	v_mfma_f32_16x16x32_bf16 v[34:37], v[168:171], v[192:195], v[34:37]
	v_mfma_f32_16x16x32_bf16 v[26:29], v[176:179], v[192:195], v[26:29]
	v_mfma_f32_16x16x32_bf16 v[18:21], v[168:171], v[200:203], v[18:21]
	v_mfma_f32_16x16x32_bf16 v[10:13], v[176:179], v[200:203], v[10:13]
	v_mfma_f32_16x16x32_bf16 v[6:9], v[168:171], v[208:211], v[6:9]
	v_mfma_f32_16x16x32_bf16 v[2:5], v[176:179], v[208:211], v[2:5]
	v_mfma_f32_16x16x32_bf16 v[50:53], v[172:175], v[188:191], v[50:53]
	v_mfma_f32_16x16x32_bf16 v[42:45], v[180:183], v[188:191], v[42:45]
	v_mfma_f32_16x16x32_bf16 v[34:37], v[172:175], v[196:199], v[34:37]
	v_mfma_f32_16x16x32_bf16 v[26:29], v[180:183], v[196:199], v[26:29]
	v_mfma_f32_16x16x32_bf16 v[18:21], v[172:175], v[204:207], v[18:21]
	v_mfma_f32_16x16x32_bf16 v[10:13], v[180:183], v[204:207], v[10:13]
	v_mfma_f32_16x16x32_bf16 v[6:9], v[172:175], v[212:215], v[6:9]
	v_mfma_f32_16x16x32_bf16 v[2:5], v[180:183], v[212:215], v[2:5]
	s_setprio 0
	s_barrier
	s_add_i32 s55, s55, 2
	s_add_u32 s24, s24, 0x100
	s_addc_u32 s25, s25, 0
	s_add_u32 s53, s53, 0x100
	s_addc_u32 s54, s54, 0
	s_cmpk_gt_u32 s55, 0x55
	s_cbranch_scc0 .LBB0_1222
	s_and_b64 vcc, exec, s[12:13]
	s_cbranch_vccz .LBB0_1225
	s_barrier
